# past: cross-lane reduction of the softmax row sum done once per group instead of per sub-tile
# baseline (speedup 1.0000x reference)
.LBB0_259:
	ds_read_b128 v[72:75], v116 offset:64
	ds_read_b128 v[100:103], v116 offset:2368
	v_mov_b32_e32 v163, v164
	v_add_u32_e32 v164, s0, v121
	s_waitcnt lgkmcnt(2)
	v_mfma_f32_16x16x32_bf16 v[198:201], v[234:237], v[40:43], 0
	v_mov_b32_e32 v165, v166
	v_add_u32_e32 v166, 0x2000, v164
	v_add_u32_e32 v167, 0x4000, v164
	v_mfma_f32_16x16x32_bf16 v[104:107], v[234:237], v[36:39], 0
	ds_read_b128 v[80:83], v116 offset:4608
	ds_read_b128 v[76:79], v116 offset:4672
	s_addk_i32 s0, 0x80
	s_cmpk_eq_i32 s0, 0x200
	v_mfma_f32_16x16x32_bf16 v[68:71], v[238:241], v[40:43], 0
	v_mfma_f32_16x16x32_bf16 v[64:67], v[238:241], v[36:39], 0
	s_waitcnt lgkmcnt(1)
	v_mfma_f32_16x16x32_bf16 v[92:95], v[80:83], v[40:43], 0
	v_mfma_f32_16x16x32_bf16 v[84:87], v[80:83], v[36:39], 0
	ds_read_b128 v[88:91], v116 offset:6912
	ds_read_b128 v[80:83], v116 offset:6976
	v_add_u32_e32 v116, 0x2400, v116
	s_waitcnt lgkmcnt(1)
	v_mfma_f32_16x16x32_bf16 v[96:99], v[88:91], v[40:43], 0
	v_mfma_f32_16x16x32_bf16 v[88:91], v[88:91], v[36:39], 0
	v_mfma_f32_16x16x32_bf16 v[68:71], v[72:75], v[44:47], v[68:71]
	v_mfma_f32_16x16x32_bf16 v[72:75], v[72:75], v[32:35], v[64:67]
	v_mfma_f32_16x16x32_bf16 v[64:67], v[100:103], v[44:47], v[198:201]
	v_mfma_f32_16x16x32_bf16 v[100:103], v[100:103], v[32:35], v[104:107]
	s_nop 2
	ds_read2_b64 v[104:107], v164 offset1:4
	ds_read2_b64 v[198:201], v164 offset0:8 offset1:12
	v_add_u32_e32 v164, 0x6000, v164
	v_mfma_f32_16x16x32_bf16 v[92:95], v[76:79], v[44:47], v[92:95]
	v_mfma_f32_16x16x32_bf16 v[76:79], v[76:79], v[32:35], v[84:87]
	s_nop 2
	ds_read2_b64 v[84:87], v166 offset0:32 offset1:36
	ds_read2_b64 v[202:205], v166 offset0:40 offset1:44
	ds_read2_b64 v[206:209], v167 offset0:64 offset1:68
	ds_read2_b64 v[210:213], v167 offset0:72 offset1:76
	ds_read2_b64 v[214:217], v164 offset0:96 offset1:100
	ds_read2_b64 v[218:221], v164 offset0:104 offset1:108
	s_waitcnt lgkmcnt(8)
	v_mfma_f32_16x16x32_bf16 v[96:99], v[80:83], v[44:47], v[96:99]
	v_mfma_f32_16x16x32_bf16 v[80:83], v[80:83], v[32:35], v[88:91]
	s_nop 2
	v_max3_f32 v88, v68, s4, v69
	v_max3_f32 v89, v72, s4, v73
	v_max3_f32 v88, v88, v70, v71
	v_max3_f32 v89, v89, v74, v75
	v_max3_f32 v88, v88, v64, v65
	v_max3_f32 v89, v89, v100, v101
	v_max3_f32 v88, v88, v66, v67
	v_max3_f32 v89, v89, v102, v103
	v_max3_f32 v88, v88, v92, v93
	v_max3_f32 v89, v89, v76, v77
	v_max3_f32 v88, v88, v94, v95
	v_max3_f32 v89, v89, v78, v79
	v_max3_f32 v88, v88, v96, v97
	v_max3_f32 v89, v89, v80, v81
	v_max3_f32 v88, v88, v98, v99
	v_max3_f32 v89, v89, v82, v83
	v_mov_b32_e32 v90, v88
	v_mov_b32_e32 v91, v89
	s_nop 0
	v_permlane16_swap_b32_e32 v90, v88
	v_permlane16_swap_b32_e32 v91, v89
	v_max_f32_e32 v88, v88, v90
	v_max_f32_e32 v89, v89, v91
	v_mov_b32_e32 v90, v88
	v_mov_b32_e32 v91, v89
	s_nop 0
	v_permlane32_swap_b32_e32 v90, v88
	v_permlane32_swap_b32_e32 v91, v89
	v_max3_f32 v164, v163, v89, v91
	v_max3_f32 v166, v165, v88, v90
	v_sub_f32_e32 v89, v163, v164
	v_sub_f32_e32 v88, v165, v166
	v_sub_f32_e32 v90, 0, v166
	v_sub_f32_e32 v178, 0, v164
	v_pk_add_f32 v[68:69], v[68:69], v[90:91] op_sel_hi:[1,0]
	v_pk_add_f32 v[70:71], v[70:71], v[90:91] op_sel_hi:[1,0]
	v_pk_add_f32 v[72:73], v[72:73], v[178:179] op_sel_hi:[1,0]
	v_pk_add_f32 v[74:75], v[74:75], v[178:179] op_sel_hi:[1,0]
	v_exp_f32_e32 v88, v88
	v_exp_f32_e32 v89, v89
	v_pk_add_f32 v[64:65], v[64:65], v[90:91] op_sel_hi:[1,0]
	v_pk_add_f32 v[66:67], v[66:67], v[90:91] op_sel_hi:[1,0]
	v_mov_b32_e32 v186, v89
	v_exp_f32_e32 v68, v68
	v_exp_f32_e32 v69, v69
	v_exp_f32_e32 v70, v70
	v_exp_f32_e32 v71, v71
	v_pk_add_f32 v[100:101], v[100:101], v[178:179] op_sel_hi:[1,0]
	v_pk_add_f32 v[102:103], v[102:103], v[178:179] op_sel_hi:[1,0]
	v_exp_f32_e32 v72, v72
	v_exp_f32_e32 v73, v73
	v_exp_f32_e32 v74, v74
	v_exp_f32_e32 v75, v75
	v_pk_mul_f32 v[60:61], v[60:61], v[88:89] op_sel_hi:[1,0]
	v_pk_mul_f32 v[62:63], v[62:63], v[88:89] op_sel_hi:[1,0]
	v_exp_f32_e32 v64, v64
	v_exp_f32_e32 v65, v65
	v_exp_f32_e32 v66, v66
	v_exp_f32_e32 v67, v67
	v_pk_mul_f32 v[56:57], v[56:57], v[88:89] op_sel_hi:[1,0]
	v_pk_mul_f32 v[58:59], v[58:59], v[88:89] op_sel_hi:[1,0]
	v_exp_f32_e32 v100, v100
	v_exp_f32_e32 v101, v101
	v_exp_f32_e32 v102, v102
	v_exp_f32_e32 v103, v103
	v_cvt_pk_bf16_f32 v222, v68, v69
	v_cvt_pk_bf16_f32 v223, v70, v71
	v_cvt_pk_bf16_f32 v224, v64, v65
	v_cvt_pk_bf16_f32 v225, v66, v67
	v_pk_mul_f32 v[28:29], v[28:29], v[186:187] op_sel_hi:[1,0]
	v_pk_mul_f32 v[30:31], v[30:31], v[186:187] op_sel_hi:[1,0]
	s_waitcnt lgkmcnt(7)
	v_mfma_f32_16x16x32_bf16 v[60:63], v[104:107], v[222:225], v[60:63]
	v_cvt_pk_bf16_f32 v226, v72, v73
	v_cvt_pk_bf16_f32 v227, v74, v75
	s_waitcnt lgkmcnt(5)
	v_mfma_f32_16x16x32_bf16 v[56:59], v[84:87], v[222:225], v[56:59]
	v_cvt_pk_bf16_f32 v228, v100, v101
	v_cvt_pk_bf16_f32 v229, v102, v103
	v_pk_mul_f32 v[24:25], v[24:25], v[186:187] op_sel_hi:[1,0]
	v_pk_mul_f32 v[26:27], v[26:27], v[186:187] op_sel_hi:[1,0]
	s_nop 1
	v_mfma_f32_16x16x32_bf16 v[28:31], v[104:107], v[226:229], v[28:31]
	v_pk_add_f32 v[92:93], v[92:93], v[90:91] op_sel_hi:[1,0]
	v_pk_add_f32 v[94:95], v[94:95], v[90:91] op_sel_hi:[1,0]
	v_pk_mul_f32 v[52:53], v[52:53], v[88:89] op_sel_hi:[1,0]
	v_pk_mul_f32 v[54:55], v[54:55], v[88:89] op_sel_hi:[1,0]
	v_mfma_f32_16x16x32_bf16 v[24:27], v[84:87], v[226:229], v[24:27]
	v_pk_add_f32 v[96:97], v[96:97], v[90:91] op_sel_hi:[1,0]
	v_pk_add_f32 v[98:99], v[98:99], v[90:91] op_sel_hi:[1,0]
	v_pk_mul_f32 v[48:49], v[48:49], v[88:89] op_sel_hi:[1,0]
	v_pk_mul_f32 v[50:51], v[50:51], v[88:89] op_sel_hi:[1,0]
	s_waitcnt lgkmcnt(3)
	v_mfma_f32_16x16x32_bf16 v[52:55], v[206:209], v[222:225], v[52:55]
	v_exp_f32_e32 v92, v92
	v_exp_f32_e32 v93, v93
	v_exp_f32_e32 v94, v94
	v_exp_f32_e32 v95, v95
	s_waitcnt lgkmcnt(1)
	v_mfma_f32_16x16x32_bf16 v[48:51], v[214:217], v[222:225], v[48:51]
	v_exp_f32_e32 v96, v96
	v_exp_f32_e32 v97, v97
	v_exp_f32_e32 v98, v98
	v_exp_f32_e32 v99, v99
	v_pk_add_f32 v[76:77], v[76:77], v[178:179] op_sel_hi:[1,0]
	v_pk_add_f32 v[78:79], v[78:79], v[178:179] op_sel_hi:[1,0]
	v_pk_add_f32 v[80:81], v[80:81], v[178:179] op_sel_hi:[1,0]
	v_pk_add_f32 v[82:83], v[82:83], v[178:179] op_sel_hi:[1,0]
	v_cvt_pk_bf16_f32 v222, v92, v93
	v_cvt_pk_bf16_f32 v223, v94, v95
	v_cvt_pk_bf16_f32 v224, v96, v97
	v_cvt_pk_bf16_f32 v225, v98, v99
	v_exp_f32_e32 v76, v76
	v_exp_f32_e32 v77, v77
	s_nop 1
	v_mfma_f32_16x16x32_bf16 v[60:63], v[198:201], v[222:225], v[60:63]
	v_exp_f32_e32 v78, v78
	v_exp_f32_e32 v79, v79
	v_mfma_f32_16x16x32_bf16 v[56:59], v[202:205], v[222:225], v[56:59]
	v_exp_f32_e32 v80, v80
	v_exp_f32_e32 v81, v81
	v_mfma_f32_16x16x32_bf16 v[52:55], v[210:213], v[222:225], v[52:55]
	v_exp_f32_e32 v82, v82
	v_exp_f32_e32 v83, v83
	s_waitcnt lgkmcnt(0)
	v_mfma_f32_16x16x32_bf16 v[48:51], v[218:221], v[222:225], v[48:51]
	ds_read_b128 v[234:237], v116 offset:2304
	ds_read_b128 v[238:241], v116
	v_pk_mul_f32 v[20:21], v[20:21], v[186:187] op_sel_hi:[1,0]
	v_pk_mul_f32 v[22:23], v[22:23], v[186:187] op_sel_hi:[1,0]
	v_pk_mul_f32 v[16:17], v[16:17], v[186:187] op_sel_hi:[1,0]
	v_pk_mul_f32 v[18:19], v[18:19], v[186:187] op_sel_hi:[1,0]
	s_nop 1
	v_mfma_f32_16x16x32_bf16 v[20:23], v[206:209], v[226:229], v[20:23]
	v_pk_add_f32 v[90:91], v[68:69], v[70:71]
	v_pk_add_f32 v[178:179], v[72:73], v[74:75]
	v_mfma_f32_16x16x32_bf16 v[16:19], v[214:217], v[226:229], v[16:19]
	v_cvt_pk_bf16_f32 v226, v76, v77
	v_cvt_pk_bf16_f32 v227, v78, v79
	v_cvt_pk_bf16_f32 v228, v80, v81
	v_cvt_pk_bf16_f32 v229, v82, v83
	v_pk_add_f32 v[90:91], v[90:91], v[64:65]
	v_pk_add_f32 v[178:179], v[178:179], v[100:101]
	s_nop 1
	v_mfma_f32_16x16x32_bf16 v[28:31], v[198:201], v[226:229], v[28:31]
	v_pk_add_f32 v[90:91], v[90:91], v[66:67]
	v_pk_add_f32 v[178:179], v[178:179], v[102:103]
	v_mfma_f32_16x16x32_bf16 v[24:27], v[202:205], v[226:229], v[24:27]
	v_pk_add_f32 v[90:91], v[90:91], v[92:93]
	v_pk_add_f32 v[178:179], v[178:179], v[76:77]
	v_mfma_f32_16x16x32_bf16 v[20:23], v[210:213], v[226:229], v[20:23]
	v_pk_add_f32 v[90:91], v[90:91], v[94:95]
	v_pk_add_f32 v[178:179], v[178:179], v[78:79]
	v_mfma_f32_16x16x32_bf16 v[16:19], v[218:221], v[226:229], v[16:19]
	v_pk_add_f32 v[90:91], v[90:91], v[96:97]
	v_pk_add_f32 v[178:179], v[178:179], v[80:81]
	v_pk_add_f32 v[90:91], v[90:91], v[98:99]
	v_pk_add_f32 v[178:179], v[178:179], v[82:83]
	v_add_f32_e32 v64, v90, v91
	v_add_f32_e32 v65, v178, v179
	v_pk_fma_f32 v[158:159], v[158:159], v[88:89], v[64:65]
	s_cmpk_lg_i32 s0, 0x80
	s_cbranch_scc1 .Lpast_qskip
	s_cmp_lg_u64 s[22:23], 0
	s_cbranch_scc1 .Lpast_qskip
	v_mov_b32_e32 v233, 0
	s_waitcnt vmcnt(1)
	v_and_b32_e32 v137, 0xfff, v141
	v_lshlrev_b32_e32 v232, 7, v137
	v_lshl_add_u64 v[4:5], v[156:157], 0, v[232:233]
	global_load_dwordx4 v[0:3], v[4:5], off
	s_nop 0
	global_load_dwordx4 v[4:7], v[4:5], off offset:64
	s_waitcnt vmcnt(2)
	v_and_b32_e32 v139, 0xfff, v149
	v_lshlrev_b32_e32 v232, 7, v139
	v_lshl_add_u64 v[12:13], v[156:157], 0, v[232:233]
	global_load_dwordx4 v[8:11], v[12:13], off
	s_nop 0
	global_load_dwordx4 v[12:15], v[12:13], off offset:64
.Lpast_qskip:
	s_cmpk_eq_i32 s0, 0x200
	s_cbranch_scc0 .LBB0_259
	v_mov_b32_e32 v66, v158
	v_mov_b32_e32 v67, v159
	s_nop 0
	v_permlane16_swap_b32_e32 v66, v158
	v_permlane16_swap_b32_e32 v67, v159
	v_pk_add_f32 v[158:159], v[158:159], v[66:67]
	s_nop 0
	v_mov_b32_e32 v66, v158
	v_mov_b32_e32 v67, v159
	s_nop 0
	v_permlane32_swap_b32_e32 v66, v158
	v_permlane32_swap_b32_e32 v67, v159
	v_pk_add_f32 v[158:159], v[158:159], v[66:67]
	s_nop 0
	s_and_saveexec_b64 s[30:31], s[28:29]
	s_cbranch_execz .LBB0_263
	v_ashrrev_i32_e32 v163, 31, v162
	v_rcp_f32_e32 v36, v158
	v_lshrrev_b32_e32 v116, 12, v161
	v_lshl_add_u64 v[34:35], s[14:15], 0, v[162:163]
	v_mad_u64_u32 v[32:33], s[28:29], v34, 3, v[116:117]
	v_mad_i32_i24 v33, v35, 3, v33
	v_lshlrev_b64 v[34:35], 7, v[32:33]
	v_pk_mul_f32 v[38:39], v[60:61], v[36:37] op_sel_hi:[1,0]
	v_pk_mul_f32 v[40:41], v[62:63], v[36:37] op_sel_hi:[1,0]
	v_cvt_pk_bf16_f32 v38, v38, v39
	v_cvt_pk_bf16_f32 v39, v40, v41
	v_lshl_add_u64 v[34:35], v[130:131], 0, v[34:35]
	global_store_dwordx2 v[34:35], v[38:39], off
	v_pk_mul_f32 v[38:39], v[36:37], v[56:57] op_sel_hi:[0,1]
	v_pk_mul_f32 v[40:41], v[36:37], v[58:59] op_sel_hi:[0,1]
	v_cvt_pk_bf16_f32 v38, v38, v39
	v_cvt_pk_bf16_f32 v39, v40, v41
	global_store_dwordx2 v[34:35], v[38:39], off offset:32
	v_pk_mul_f32 v[38:39], v[36:37], v[52:53] op_sel_hi:[0,1]
	v_pk_mul_f32 v[40:41], v[36:37], v[54:55] op_sel_hi:[0,1]
	v_cvt_pk_bf16_f32 v38, v38, v39
	v_cvt_pk_bf16_f32 v39, v40, v41
	global_store_dwordx2 v[34:35], v[38:39], off offset:64
	v_pk_mul_f32 v[38:39], v[36:37], v[48:49] op_sel_hi:[0,1]
	v_pk_mul_f32 v[36:37], v[36:37], v[50:51] op_sel_hi:[0,1]
	v_cvt_pk_bf16_f32 v38, v38, v39
	v_cvt_pk_bf16_f32 v39, v36, v37
	global_store_dwordx2 v[34:35], v[38:39], off offset:96
	s_and_b64 exec, exec, s[8:9]
	s_cbranch_execz .LBB0_263
	v_lshl_add_u64 v[32:33], v[32:33], 3, s[42:43]
	v_mov_b32_e32 v167, v158
	global_store_dwordx2 v[32:33], v[166:167], off sc1
